# gla_s3: next chunk's AG fragments issued right after the A.v MFMAs and its v fragments right after the state-update MFMAs that last read them (loop-slack prefetch, counted vmcnt 8/14/10)
# baseline (speedup 1.0000x reference)
.LBB0_739:
	s_ashr_i32 s11, s10, 31
	s_lshl_b64 s[4:5], s[10:11], 13
	v_lshl_add_u64 v[64:65], v[212:213], 0, s[4:5]
	s_lshl_b64 s[4:5], s[10:11], 16
	v_lshl_add_u64 v[66:67], v[216:217], 0, s[4:5]
	s_cmp_lg_u32 s12, 0
	s_cbranch_scc1 .Lmy_s3_skipA
	global_load_dwordx4 v[144:147], v[64:65], off
	global_load_dwordx4 v[148:151], v[64:65], off offset:32
	global_load_dwordx4 v[140:143], v[66:67], off
	global_load_dwordx4 v[136:139], v[66:67], off offset:1024
	global_load_dwordx4 v[152:155], v[64:65], off offset:64
	global_load_dwordx4 v[156:159], v[64:65], off offset:96
	global_load_dwordx4 v[132:135], v[66:67], off offset:2048
	global_load_dwordx4 v[128:131], v[66:67], off offset:3072
.Lmy_s3_skipA:
	s_cmp_lg_u32 s12, 0x1c0000
	s_cselect_b64 s[14:15], -1, 0
	s_cmp_eq_u32 s12, 0x1c0000
	s_cbranch_scc1 .LBB0_741
	s_add_i32 s4, s10, 4
	s_ashr_i32 s5, s4, 31
	s_lshl_b64 s[4:5], s[4:5], 15
	v_lshl_add_u64 v[64:65], v[170:171], 0, s[4:5]
	v_add_co_u32_e32 v66, vcc, 0x2000, v64
	s_nop 1
	v_addc_co_u32_e32 v67, vcc, 0, v65, vcc
	global_load_dwordx4 v[96:99], v[64:65], off
	global_load_dwordx4 v[104:107], v[66:67], off
	v_add_co_u32_e32 v66, vcc, 0x4000, v64
	s_nop 1
	v_addc_co_u32_e32 v67, vcc, 0, v65, vcc
	v_add_co_u32_e32 v64, vcc, 0x6000, v64
	s_nop 1
	v_addc_co_u32_e32 v65, vcc, 0, v65, vcc
	global_load_dwordx4 v[112:115], v[66:67], off
	global_load_dwordx4 v[120:123], v[64:65], off

.LBB0_747:
	v_cndmask_b32_e64 v64, v80, v64, s[6:7]
	v_cndmask_b32_e64 v65, v81, v65, s[6:7]
	v_cndmask_b32_e64 v66, v82, v66, s[6:7]
	v_cndmask_b32_e64 v67, v83, v67, s[6:7]
	v_cndmask_b32_e64 v68, v84, v68, s[6:7]
	v_cndmask_b32_e64 v69, v85, v69, s[6:7]
	v_cndmask_b32_e64 v70, v86, v70, s[6:7]
	v_cndmask_b32_e64 v71, v87, v71, s[6:7]
	v_cndmask_b32_e64 v72, v88, v72, s[6:7]
	v_cndmask_b32_e64 v73, v89, v73, s[6:7]
	v_cndmask_b32_e64 v74, v90, v74, s[6:7]
	v_cndmask_b32_e64 v75, v91, v75, s[6:7]
	v_cndmask_b32_e64 v76, v92, v76, s[6:7]
	v_cndmask_b32_e64 v77, v93, v77, s[6:7]
	v_cndmask_b32_e64 v78, v94, v78, s[6:7]
	v_cndmask_b32_e64 v79, v95, v79, s[6:7]
	s_waitcnt lgkmcnt(0)
	v_add_f32_e32 v64, v64, v234
	v_add_f32_e32 v65, v65, v235
	v_add_f32_e32 v66, v66, v232
	v_add_f32_e32 v67, v67, v233
	v_add_f32_e32 v68, v68, v230
	v_add_f32_e32 v69, v69, v231
	v_add_f32_e32 v70, v70, v228
	v_add_f32_e32 v71, v71, v229
	v_add_f32_e32 v72, v72, v226
	v_add_f32_e32 v73, v73, v227
	v_add_f32_e32 v74, v74, v224
	v_add_f32_e32 v75, v75, v225
	v_add_f32_e32 v76, v76, v222
	v_add_f32_e32 v77, v77, v223
	v_add_f32_e32 v78, v78, v220
	v_add_f32_e32 v79, v79, v221
	s_mov_b32 s14, 0x2ec00000
	v_add_u32_e32 v92, s21, v210
	s_waitcnt vmcnt(8)
	v_mfma_f32_32x32x16_bf16 v[64:79], v[144:147], v[140:143], v[64:79]
	v_mfma_f32_32x32x16_bf16 v[64:79], v[148:151], v[136:139], v[64:79]
	v_mfma_f32_32x32x16_bf16 v[64:79], v[152:155], v[132:135], v[64:79]
	v_mfma_f32_32x32x16_bf16 v[64:79], v[156:159], v[128:131], v[64:79]
	s_and_b64 vcc, exec, s[4:5]
	s_cbranch_vccnz .Lmy_s3_noA1
	s_add_i32 s16, s10, 4
	s_ashr_i32 s17, s16, 31
	s_lshl_b64 s[16:17], s[16:17], 13
	v_lshl_add_u64 v[246:247], v[212:213], 0, s[16:17]
	global_load_dwordx4 v[144:147], v[246:247], off
	global_load_dwordx4 v[148:151], v[246:247], off offset:32
	global_load_dwordx4 v[152:155], v[246:247], off offset:64
	global_load_dwordx4 v[156:159], v[246:247], off offset:96
	s_lshl_b64 s[16:17], s[16:17], 3
	v_lshl_add_u64 v[246:247], v[216:217], 0, s[16:17]
.Lmy_s3_noA1:
	s_nop 11
	v_cvt_pk_bf16_f32 v80, v64, v65
	v_cvt_pk_bf16_f32 v81, v66, v67
	v_cvt_pk_bf16_f32 v82, v68, v69
	v_cvt_pk_bf16_f32 v83, v70, v71
	v_cvt_pk_bf16_f32 v84, v72, v73
	v_cvt_pk_bf16_f32 v85, v74, v75
	v_cvt_pk_bf16_f32 v86, v76, v77
	v_cvt_pk_bf16_f32 v87, v78, v79
	ds_write_b16 v244, v80
	ds_write_b16_d16_hi v244, v80 offset:80
	ds_write_b16 v244, v81 offset:160
	ds_write_b16_d16_hi v244, v81 offset:240
	ds_write_b16 v244, v82 offset:640
	ds_write_b16_d16_hi v244, v82 offset:720
	ds_write_b16 v244, v83 offset:800
	ds_write_b16_d16_hi v244, v83 offset:880
	ds_write_b16 v244, v84 offset:1280
	ds_write_b16_d16_hi v244, v84 offset:1360
	ds_write_b16 v244, v85 offset:1440
	ds_write_b16_d16_hi v244, v85 offset:1520
	ds_write_b16 v244, v86 offset:1920
	ds_write_b16_d16_hi v244, v86 offset:2000
	ds_write_b16 v244, v87 offset:2080
	ds_write_b16_d16_hi v244, v87 offset:2160
	v_lshl_add_u64 v[88:89], v[242:243], 0, s[12:13]
	s_mov_b32 s14, 0x2ec00000
	v_add_co_u32_e32 v88, vcc, s14, v88
	s_nop 1
	v_addc_co_u32_e32 v89, vcc, 0, v89, vcc
	ds_read_b128 v[64:67], v245
	ds_read_b128 v[68:71], v245 offset:1280
	v_add_co_u32_e32 v90, vcc, 0x10000, v88
	s_nop 1
	v_addc_co_u32_e32 v91, vcc, 0, v89, vcc
	s_waitcnt lgkmcnt(0)
	global_store_dwordx4 v[88:89], v[64:67], off
	global_store_dwordx4 v[90:91], v[68:71], off
	s_and_b64 vcc, exec, s[4:5]
	ds_read_b128 v[64:67], v92
	ds_read_b128 v[68:71], v92 offset:32
	ds_read_b128 v[72:75], v92 offset:64
	ds_read_b128 v[76:79], v92 offset:96
	ds_read_b128 v[80:83], v92 offset:128
	ds_read_b128 v[84:87], v92 offset:160
	ds_read_b128 v[88:91], v92 offset:192
	ds_read_b128 v[220:223], v92 offset:224
	s_waitcnt lgkmcnt(4)
	v_pk_mul_f32 v[0:1], v[0:1], v[64:65]
	v_pk_mul_f32 v[2:3], v[2:3], v[66:67]
	v_pk_mul_f32 v[4:5], v[4:5], v[68:69]
	v_pk_mul_f32 v[6:7], v[6:7], v[70:71]
	v_pk_mul_f32 v[8:9], v[8:9], v[72:73]
	v_pk_mul_f32 v[10:11], v[10:11], v[74:75]
	v_pk_mul_f32 v[12:13], v[12:13], v[76:77]
	v_pk_mul_f32 v[14:15], v[14:15], v[78:79]
	ds_read_b128 v[64:67], v92 offset:256
	ds_read_b128 v[68:71], v92 offset:288
	ds_read_b128 v[72:75], v92 offset:320
	ds_read_b128 v[76:79], v92 offset:352
	s_waitcnt lgkmcnt(4)
	v_pk_mul_f32 v[16:17], v[16:17], v[80:81]
	v_pk_mul_f32 v[18:19], v[18:19], v[82:83]
	v_pk_mul_f32 v[20:21], v[20:21], v[84:85]
	v_pk_mul_f32 v[22:23], v[22:23], v[86:87]
	v_pk_mul_f32 v[24:25], v[24:25], v[88:89]
	v_pk_mul_f32 v[26:27], v[26:27], v[90:91]
	v_pk_mul_f32 v[28:29], v[28:29], v[220:221]
	v_pk_mul_f32 v[30:31], v[30:31], v[222:223]
	ds_read_b128 v[80:83], v92 offset:384
	ds_read_b128 v[84:87], v92 offset:416
	ds_read_b128 v[88:91], v92 offset:448
	ds_read_b128 v[220:223], v92 offset:480
	s_waitcnt lgkmcnt(4)
	v_pk_mul_f32 v[32:33], v[32:33], v[64:65]
	v_pk_mul_f32 v[34:35], v[34:35], v[66:67]
	v_pk_mul_f32 v[36:37], v[36:37], v[68:69]
	v_pk_mul_f32 v[38:39], v[38:39], v[70:71]
	v_pk_mul_f32 v[40:41], v[40:41], v[72:73]
	v_pk_mul_f32 v[42:43], v[42:43], v[74:75]
	v_pk_mul_f32 v[44:45], v[44:45], v[76:77]
	v_pk_mul_f32 v[46:47], v[46:47], v[78:79]
	ds_read_b128 v[64:67], v199
	ds_read_b128 v[68:71], v199 offset:4096
	ds_read_b128 v[72:75], v199 offset:8192
	ds_read_b128 v[76:79], v199 offset:12288
	s_waitcnt lgkmcnt(4)
	v_pk_mul_f32 v[48:49], v[48:49], v[80:81]
	v_pk_mul_f32 v[50:51], v[50:51], v[82:83]
	v_pk_mul_f32 v[52:53], v[52:53], v[84:85]
	v_pk_mul_f32 v[54:55], v[54:55], v[86:87]
	v_pk_mul_f32 v[56:57], v[56:57], v[88:89]
	v_pk_mul_f32 v[58:59], v[58:59], v[90:91]
	v_pk_mul_f32 v[60:61], v[60:61], v[220:221]
	v_pk_mul_f32 v[62:63], v[62:63], v[222:223]
	s_waitcnt lgkmcnt(3)
	v_mfma_f32_32x32x16_bf16 v[0:15], v[64:67], v[140:143], v[0:15]
	ds_read_b128 v[64:67], v199 offset:1024
	s_waitcnt lgkmcnt(3)
	v_mfma_f32_32x32x16_bf16 v[16:31], v[68:71], v[140:143], v[16:31]
	ds_read_b128 v[68:71], v199 offset:5120
	s_waitcnt lgkmcnt(3)
	v_mfma_f32_32x32x16_bf16 v[32:47], v[72:75], v[140:143], v[32:47]
	ds_read_b128 v[72:75], v199 offset:9216
	s_waitcnt lgkmcnt(3)
	v_mfma_f32_32x32x16_bf16 v[48:63], v[76:79], v[140:143], v[48:63]
	s_cbranch_vccnz .Lmy_s3_nv0
	global_load_dwordx4 v[140:143], v[246:247], off
.Lmy_s3_nv0:
	ds_read_b128 v[76:79], v199 offset:13312
	s_waitcnt lgkmcnt(3)
	v_mfma_f32_32x32x16_bf16 v[0:15], v[64:67], v[136:139], v[0:15]
	ds_read_b128 v[64:67], v199 offset:2048
	s_waitcnt lgkmcnt(3)
	v_mfma_f32_32x32x16_bf16 v[16:31], v[68:71], v[136:139], v[16:31]
	ds_read_b128 v[68:71], v199 offset:6144
	s_waitcnt lgkmcnt(3)
	v_mfma_f32_32x32x16_bf16 v[32:47], v[72:75], v[136:139], v[32:47]
	ds_read_b128 v[72:75], v199 offset:10240
	s_waitcnt lgkmcnt(3)
	v_mfma_f32_32x32x16_bf16 v[48:63], v[76:79], v[136:139], v[48:63]
	s_cbranch_vccnz .Lmy_s3_nv1
	global_load_dwordx4 v[136:139], v[246:247], off offset:1024
.Lmy_s3_nv1:
	ds_read_b128 v[76:79], v199 offset:14336
	s_waitcnt lgkmcnt(3)
	v_mfma_f32_32x32x16_bf16 v[0:15], v[64:67], v[132:135], v[0:15]
	ds_read_b128 v[64:67], v199 offset:3072
	s_waitcnt lgkmcnt(3)
	v_mfma_f32_32x32x16_bf16 v[16:31], v[68:71], v[132:135], v[16:31]
	ds_read_b128 v[68:71], v199 offset:7168
	s_waitcnt lgkmcnt(3)
	v_mfma_f32_32x32x16_bf16 v[32:47], v[72:75], v[132:135], v[32:47]
	ds_read_b128 v[72:75], v199 offset:11264
	s_waitcnt lgkmcnt(3)
	v_mfma_f32_32x32x16_bf16 v[48:63], v[76:79], v[132:135], v[48:63]
	s_cbranch_vccnz .Lmy_s3_nv2
	global_load_dwordx4 v[132:135], v[246:247], off offset:2048
.Lmy_s3_nv2:
	ds_read_b128 v[76:79], v199 offset:15360
	s_waitcnt lgkmcnt(3)
	v_mfma_f32_32x32x16_bf16 v[0:15], v[64:67], v[128:131], v[0:15]
	s_waitcnt lgkmcnt(2)
	v_mfma_f32_32x32x16_bf16 v[16:31], v[68:71], v[128:131], v[16:31]
	s_waitcnt lgkmcnt(1)
	v_mfma_f32_32x32x16_bf16 v[32:47], v[72:75], v[128:131], v[32:47]
	s_waitcnt lgkmcnt(0)
	v_mfma_f32_32x32x16_bf16 v[48:63], v[76:79], v[128:131], v[48:63]
	s_cbranch_vccnz .Lmy_s3_nv3
	global_load_dwordx4 v[128:131], v[246:247], off offset:3072
.Lmy_s3_nv3:
	s_cbranch_vccnz .LBB0_738
	s_xor_b32 s4, s11, 0x8000
	v_add_u32_e32 v64, s4, v177
	s_waitcnt vmcnt(14)
	ds_write_b128 v64, v[96:99]
	ds_write_b128 v64, v[104:107] offset:8192
	ds_write_b128 v64, v[112:115] offset:16384
	ds_write_b128 v64, v[120:123] offset:24576
	s_branch .LBB0_738
